# attA unit boundary: trailing s_barrier of the output store block removed (the pop broadcast's first barrier follows with only thread 0's slot write in between), on top of the no-store-wait pop
# speedup vs baseline: 1.0029x; 1.0029x over previous
; #define LAS __attribute__((address_space(3)))
; __device__ __forceinline__ void unit(LAS unsigned char* lds, bf16_t* P1, const bf16_t* vaT, int b, int h, int qblk, float lam, const float* subln_w, const float* khalf) {
;     ...
;     __syncthreads();
;     { bf16_t* ob_ = P1 + (rowbase + (size_t)qblk * 128) * LDP + C_QA + h * 128;
; #pragma unroll
;       for (int i = 0; i < 4; ++i) { const int idx = tid + 512 * i, row = idx >> 4, ch = idx & 15;
;           const u32x4 v = *(const LAS u32x4*)(lds + 69632 + row * 272 + ch * 16);
;           *(u32x4*)(ob_ + (size_t)row * LDP + ch * 8) = v; } }
;     __syncthreads();
.LBB0_383:
	s_or_b32 s2, s60, s59
	s_mulk_i32 s2, 0x3400
	s_add_u32 s2, s78, s2
	s_waitcnt lgkmcnt(0)
	s_barrier
	s_addc_u32 s3, s79, 0
	ds_read_b128 v[2:5], v181
	s_add_u32 s2, s2, s42
	s_addc_u32 s3, s3, s43
	v_mov_b32_e32 v123, v1
	v_lshl_add_u64 v[14:15], s[2:3], 0, v[122:123]
	v_mov_b32_e32 v125, v1
	ds_read_b128 v[6:9], v182
	ds_read_b128 v[10:13], v181 offset:17408
	v_lshl_add_u64 v[16:17], v[14:15], 0, v[124:125]
	s_waitcnt lgkmcnt(2)
	global_store_dwordx4 v[16:17], v[2:5], off
	v_mov_b32_e32 v127, v1
	ds_read_b128 v[2:5], v183
	v_lshl_add_u64 v[18:19], v[14:15], 0, v[126:127]
	s_waitcnt lgkmcnt(2)
	global_store_dwordx4 v[18:19], v[6:9], off
	v_mov_b32_e32 v129, v1
	s_mov_b64 s[2:3], 0
	v_add_co_u32_e32 v6, vcc, 0xd0000, v16
	s_nop 1
	v_addc_co_u32_e32 v7, vcc, 0, v17, vcc
	s_waitcnt lgkmcnt(1)
	global_store_dwordx4 v[6:7], v[10:13], off
	v_lshl_add_u64 v[6:7], v[14:15], 0, v[128:129]
	s_waitcnt lgkmcnt(0)
	global_store_dwordx4 v[6:7], v[2:5], off
.LBB0_384:
	s_and_b64 vcc, exec, s[2:3]
	s_cbranch_vccnz .LBB0_381
	s_and_saveexec_b64 s[2:3], s[8:9]
	s_cbranch_execz .LBB0_389
	v_mov_b32_e32 v0, 0
	s_branch .La_pop_ready
